# current best plus removal of the redundant lgkmcnt(0) right after each GEMM segment barrier
# speedup vs baseline: 1.0050x; 1.0050x over previous
; #define PG8_STAGE(bufoff, gbase, voff) do { _Pragma("unroll") for (int _i = 0; _i < 2; ++_i) \
;         __builtin_amdgcn_global_load_lds((const unsigned*)((const char*)(gbase) + (voff)[_i]), (LAS unsigned*)(lds + (bufoff) + ldsw + _i * 8192), 16, 0, 0); } while (0)
; #define PG8_LDA(dst, b, h) do { _Pragma("unroll") for (int m = 0; m < 4; ++m) _Pragma("unroll") for (int k = 0; k < 2; ++k) dst[m][k] = *(const LAS bf16x8*)(lds + PG8_SA(b, h) + aoff + m * 2048 + k * 1024); } while (0)
; #define PG8_LDB(dst, b, h) do { _Pragma("unroll") for (int n = 0; n < 2; ++n) _Pragma("unroll") for (int k = 0; k < 2; ++k) dst[n][k] = *(const LAS bf16x8*)(lds + PG8_SB(b, h) + boff + n * 2048 + k * 1024); } while (0)
; #define PG8_MMA(ai, bj, At, Bt) do { __builtin_amdgcn_s_setprio(1); _Pragma("unroll") for (int m = 0; m < 4; ++m) _Pragma("unroll") for (int n = 0; n < 2; ++n) _Pragma("unroll") for (int k = 0; k < 2; ++k) \
;         acc[ai][bj][m][n] = __builtin_amdgcn_mfma_f32_16x16x32_bf16(Bt[n][k], At[m][k], acc[ai][bj][m][n], 0, 0, 0); __builtin_amdgcn_s_setprio(0); } while (0)
; #define PG8_WAIT_V(n) asm volatile("s_waitcnt vmcnt(" #n ")" ::: "memory")
; #define PG8_WAIT_L(n) asm volatile("s_waitcnt lgkmcnt(" #n ")" ::: "memory")
; #define PG8_BAR __builtin_amdgcn_s_barrier()
; #define PG8_SCHED __builtin_amdgcn_sched_barrier(0)
; __device__ __forceinline__ void gemm_phase(LAS unsigned char* lds, const GemmD g, const Sched& S, const Epi& E) {
;     ...
;             const bool last = (t == nt - 2);
;             const char* a1 = cA + (size_t)(t + 1) * kstep;
;             const char* a2 = last ? nA : cA + (size_t)(t + 2) * kstep; const char* b2 = last ? nB : cB + (size_t)(t + 2) * kstep;
;             const char* a3 = a2 + kstep; const char* b3 = b2 + kstep;
;             PG8_LDB(B0, 0, 0); PG8_LDB(B1, 0, 1); PG8_SCHED; PG8_LDA(At, 0, 0); PG8_STAGE(PG8_SA(1, 1), a1 + hstepA, voffA);
;             PG8_WAIT_V(8); PG8_WAIT_L(0); PG8_BAR; PG8_MMA(0, 0, At, B0); PG8_MMA(0, 1, At, B1); PG8_BAR; PG8_SCHED;
;             PG8_LDA(At, 0, 1); PG8_STAGE(PG8_SB(0, 0), b2, voffB); PG8_STAGE(PG8_SB(0, 1), b2 + hstepB, voffB); PG8_STAGE(PG8_SA(0, 0), a2, voffA);
;             PG8_WAIT_V(8); PG8_WAIT_L(0); PG8_BAR; PG8_MMA(1, 0, At, B0); PG8_MMA(1, 1, At, B1); PG8_BAR; PG8_SCHED;
.Lprio_done:
	v_add_u32_e32 v240, 0x10000, v160
	v_add_u32_e32 v241, 0x14000, v160
	v_add_u32_e32 v242, 0x18000, v160
	v_add_u32_e32 v243, 0x1c000, v160
	ds_read_b128 v[130:133], v240
	ds_read_b128 v[146:149], v240 offset:1024
	ds_read_b128 v[150:153], v240 offset:2048
	ds_read_b128 v[154:157], v240 offset:3072
	ds_read_b128 v[162:165], v241
	ds_read_b128 v[166:169], v241 offset:1024
	ds_read_b128 v[170:173], v241 offset:2048
	ds_read_b128 v[174:177], v241 offset:3072
	s_add_i32 m0, s31, 0xc000
	ds_read_b128 v[182:185], v161
	ds_read_b128 v[186:189], v161 offset:1024
	ds_read_b128 v[190:193], v161 offset:2048
	ds_read_b128 v[216:219], v161 offset:3072
	ds_read_b128 v[220:223], v161 offset:4096
	ds_read_b128 v[224:227], v161 offset:5120
	ds_read_b128 v[228:231], v161 offset:6144
	ds_read_b128 v[236:239], v161 offset:7168
	global_load_lds_dwordx4 v142, s[8:9]
	s_add_i32 m0, s31, 0xe000
	s_nop 0
	global_load_lds_dwordx4 v144, s[8:9]
	s_add_i32 s92, s26, 2
	s_add_u32 s93, s8, 0x80
	s_addc_u32 s27, s9, 0
	s_add_i32 s22, 0, 0x10000
	s_cmp_eq_u32 s11, s26
	s_cselect_b32 s27, s1, s27
	s_cselect_b32 s26, s0, s93
	s_cselect_b32 vcc_hi, s17, s35
	s_cselect_b32 vcc_lo, s16, s34
	s_add_i32 s23, 0, 0x14000
	s_waitcnt vmcnt(8)
	s_waitcnt lgkmcnt(0)
	s_barrier
	v_mfma_f32_16x16x32_bf16 v[126:129], v[130:133], v[182:185], 0
	v_mfma_f32_16x16x32_bf16 v[122:125], v[150:153], v[182:185], 0
	v_mfma_f32_16x16x32_bf16 v[110:113], v[130:133], v[190:193], 0
	v_mfma_f32_16x16x32_bf16 v[106:109], v[150:153], v[190:193], 0
	v_mfma_f32_16x16x32_bf16 v[94:97], v[130:133], v[220:223], 0
	v_mfma_f32_16x16x32_bf16 v[90:93], v[150:153], v[220:223], 0
	v_mfma_f32_16x16x32_bf16 v[78:81], v[130:133], v[228:231], 0
	v_mfma_f32_16x16x32_bf16 v[74:77], v[150:153], v[228:231], 0
	v_mfma_f32_16x16x32_bf16 v[126:129], v[146:149], v[186:189], v[126:129]
	v_mfma_f32_16x16x32_bf16 v[122:125], v[154:157], v[186:189], v[122:125]
	v_mfma_f32_16x16x32_bf16 v[110:113], v[146:149], v[216:219], v[110:113]
	v_mfma_f32_16x16x32_bf16 v[106:109], v[154:157], v[216:219], v[106:109]
	v_mfma_f32_16x16x32_bf16 v[94:97], v[146:149], v[224:227], v[94:97]
	v_mfma_f32_16x16x32_bf16 v[90:93], v[154:157], v[224:227], v[90:93]
	v_mfma_f32_16x16x32_bf16 v[78:81], v[146:149], v[236:239], v[78:81]
	v_mfma_f32_16x16x32_bf16 v[74:77], v[154:157], v[236:239], v[74:77]
	v_mfma_f32_16x16x32_bf16 v[118:121], v[162:165], v[182:185], 0
	v_mfma_f32_16x16x32_bf16 v[114:117], v[170:173], v[182:185], 0
	v_mfma_f32_16x16x32_bf16 v[102:105], v[162:165], v[190:193], 0
	v_mfma_f32_16x16x32_bf16 v[98:101], v[170:173], v[190:193], 0
	v_mfma_f32_16x16x32_bf16 v[86:89], v[162:165], v[220:223], 0
	v_mfma_f32_16x16x32_bf16 v[82:85], v[170:173], v[220:223], 0
	v_mfma_f32_16x16x32_bf16 v[70:73], v[162:165], v[228:231], 0
	v_mfma_f32_16x16x32_bf16 v[66:69], v[170:173], v[228:231], 0
	v_mfma_f32_16x16x32_bf16 v[118:121], v[166:169], v[186:189], v[118:121]
	v_mfma_f32_16x16x32_bf16 v[114:117], v[174:177], v[186:189], v[114:117]
	v_mfma_f32_16x16x32_bf16 v[102:105], v[166:169], v[216:219], v[102:105]
	v_mfma_f32_16x16x32_bf16 v[98:101], v[174:177], v[216:219], v[98:101]
	v_mfma_f32_16x16x32_bf16 v[86:89], v[166:169], v[224:227], v[86:89]
	v_mfma_f32_16x16x32_bf16 v[82:85], v[174:177], v[224:227], v[82:85]
	v_mfma_f32_16x16x32_bf16 v[70:73], v[166:169], v[236:239], v[70:73]
	v_mfma_f32_16x16x32_bf16 v[66:69], v[174:177], v[236:239], v[66:69]
	s_barrier
	s_add_i32 s22, s22, s30
	s_mov_b32 m0, s22
	ds_read_b128 v[182:185], v161 offset:16384
	ds_read_b128 v[186:189], v161 offset:17408
	ds_read_b128 v[190:193], v161 offset:18432
	ds_read_b128 v[216:219], v161 offset:19456
	ds_read_b128 v[220:223], v161 offset:20480
	ds_read_b128 v[224:227], v161 offset:21504
	ds_read_b128 v[228:231], v161 offset:22528
	ds_read_b128 v[236:239], v161 offset:23552
	global_load_lds_dwordx4 v136, vcc
	s_add_i32 m0, s22, 0x2000
	s_add_i32 s22, s23, s30
	global_load_lds_dwordx4 v140, vcc
	s_mov_b32 m0, s22
	s_nop 0
	global_load_lds_dwordx4 v253, vcc
	s_add_i32 m0, s22, 0x2000
	s_nop 0
	global_load_lds_dwordx4 v254, vcc
	s_mov_b32 m0, s31
	s_add_u32 s34, s34, 0x100
	global_load_lds_dwordx4 v134, s[26:27]
	s_mov_b32 m0, s14
	s_addc_u32 s35, s35, 0
	global_load_lds_dwordx4 v138, s[26:27]
	s_waitcnt vmcnt(8)
	s_waitcnt lgkmcnt(0)
	s_barrier
	v_mfma_f32_16x16x32_bf16 v[62:65], v[130:133], v[182:185], 0
	v_mfma_f32_16x16x32_bf16 v[58:61], v[150:153], v[182:185], 0
	v_mfma_f32_16x16x32_bf16 v[46:49], v[130:133], v[190:193], 0
	v_mfma_f32_16x16x32_bf16 v[42:45], v[150:153], v[190:193], 0
	v_mfma_f32_16x16x32_bf16 v[30:33], v[130:133], v[220:223], 0
	v_mfma_f32_16x16x32_bf16 v[26:29], v[150:153], v[220:223], 0
	v_mfma_f32_16x16x32_bf16 v[14:17], v[130:133], v[228:231], 0
	v_mfma_f32_16x16x32_bf16 v[10:13], v[150:153], v[228:231], 0
	v_mfma_f32_16x16x32_bf16 v[62:65], v[146:149], v[186:189], v[62:65]
	v_mfma_f32_16x16x32_bf16 v[58:61], v[154:157], v[186:189], v[58:61]
	v_mfma_f32_16x16x32_bf16 v[46:49], v[146:149], v[216:219], v[46:49]
	v_mfma_f32_16x16x32_bf16 v[42:45], v[154:157], v[216:219], v[42:45]
	v_mfma_f32_16x16x32_bf16 v[30:33], v[146:149], v[224:227], v[30:33]
	v_mfma_f32_16x16x32_bf16 v[26:29], v[154:157], v[224:227], v[26:29]
	v_mfma_f32_16x16x32_bf16 v[14:17], v[146:149], v[236:239], v[14:17]
	v_mfma_f32_16x16x32_bf16 v[10:13], v[154:157], v[236:239], v[10:13]
	v_mfma_f32_16x16x32_bf16 v[54:57], v[162:165], v[182:185], 0
	v_mfma_f32_16x16x32_bf16 v[50:53], v[170:173], v[182:185], 0
	v_mfma_f32_16x16x32_bf16 v[38:41], v[162:165], v[190:193], 0
	v_mfma_f32_16x16x32_bf16 v[34:37], v[170:173], v[190:193], 0
	v_mfma_f32_16x16x32_bf16 v[22:25], v[162:165], v[220:223], 0
	v_mfma_f32_16x16x32_bf16 v[18:21], v[170:173], v[220:223], 0
	v_mfma_f32_16x16x32_bf16 v[6:9], v[162:165], v[228:231], 0
	v_mfma_f32_16x16x32_bf16 v[2:5], v[170:173], v[228:231], 0
	v_mfma_f32_16x16x32_bf16 v[54:57], v[166:169], v[186:189], v[54:57]
	v_mfma_f32_16x16x32_bf16 v[50:53], v[174:177], v[186:189], v[50:53]
	v_mfma_f32_16x16x32_bf16 v[38:41], v[166:169], v[216:219], v[38:41]
	v_mfma_f32_16x16x32_bf16 v[34:37], v[174:177], v[216:219], v[34:37]
	v_mfma_f32_16x16x32_bf16 v[22:25], v[166:169], v[224:227], v[22:25]
	v_mfma_f32_16x16x32_bf16 v[18:21], v[174:177], v[224:227], v[18:21]
	v_mfma_f32_16x16x32_bf16 v[6:9], v[166:169], v[236:239], v[6:9]
	v_mfma_f32_16x16x32_bf16 v[2:5], v[174:177], v[236:239], v[2:5]
	s_barrier
; #define PG8_STAGE(bufoff, gbase, voff) do { _Pragma("unroll") for (int _i = 0; _i < 2; ++_i) \
;         __builtin_amdgcn_global_load_lds((const unsigned*)((const char*)(gbase) + (voff)[_i]), (LAS unsigned*)(lds + (bufoff) + ldsw + _i * 8192), 16, 0, 0); } while (0)
; #define PG8_LDA(dst, b, h) do { _Pragma("unroll") for (int m = 0; m < 4; ++m) _Pragma("unroll") for (int k = 0; k < 2; ++k) dst[m][k] = *(const LAS bf16x8*)(lds + PG8_SA(b, h) + aoff + m * 2048 + k * 1024); } while (0)
; #define PG8_LDB(dst, b, h) do { _Pragma("unroll") for (int n = 0; n < 2; ++n) _Pragma("unroll") for (int k = 0; k < 2; ++k) dst[n][k] = *(const LAS bf16x8*)(lds + PG8_SB(b, h) + boff + n * 2048 + k * 1024); } while (0)
; #define PG8_MMA(ai, bj, At, Bt) do { __builtin_amdgcn_s_setprio(1); _Pragma("unroll") for (int m = 0; m < 4; ++m) _Pragma("unroll") for (int n = 0; n < 2; ++n) _Pragma("unroll") for (int k = 0; k < 2; ++k) \
;         acc[ai][bj][m][n] = __builtin_amdgcn_mfma_f32_16x16x32_bf16(Bt[n][k], At[m][k], acc[ai][bj][m][n], 0, 0, 0); __builtin_amdgcn_s_setprio(0); } while (0)
; #define PG8_WAIT_V(n) asm volatile("s_waitcnt vmcnt(" #n ")" ::: "memory")
; #define PG8_WAIT_L(n) asm volatile("s_waitcnt lgkmcnt(" #n ")" ::: "memory")
; #define PG8_BAR __builtin_amdgcn_s_barrier()
; #define PG8_SCHED __builtin_amdgcn_sched_barrier(0)
; __device__ __forceinline__ void gemm_phase(LAS unsigned char* lds, const GemmD g, const Sched& S, const Epi& E) {
;     ...
;             PG8_LDB(B0, 1, 0); PG8_LDB(B1, 1, 1); PG8_SCHED; PG8_LDA(At, 1, 0); PG8_STAGE(PG8_SA(0, 1), a2 + hstepA, voffA);
;             PG8_WAIT_V(8); PG8_WAIT_L(0); PG8_BAR; PG8_MMA(0, 0, At, B0); PG8_MMA(0, 1, At, B1); PG8_BAR; PG8_SCHED;
;             PG8_LDA(At, 1, 1); PG8_STAGE(PG8_SB(1, 0), b3, voffB); PG8_STAGE(PG8_SB(1, 1), b3 + hstepB, voffB); PG8_STAGE(PG8_SA(1, 0), a3, voffA);
;             PG8_WAIT_V(8); PG8_WAIT_L(0); PG8_BAR; PG8_MMA(1, 0, At, B0); PG8_MMA(1, 1, At, B1); PG8_BAR; PG8_SCHED;
;         }
	s_add_i32 s22, 0, 0x18000
	s_add_i32 s23, 0, 0x1c000
	ds_read_b128 v[130:133], v242
	ds_read_b128 v[146:149], v242 offset:1024
	ds_read_b128 v[150:153], v242 offset:2048
	ds_read_b128 v[154:157], v242 offset:3072
	ds_read_b128 v[162:165], v243
	ds_read_b128 v[166:169], v243 offset:1024
	ds_read_b128 v[170:173], v243 offset:2048
	ds_read_b128 v[174:177], v243 offset:3072
	s_mov_b32 m0, s15
	ds_read_b128 v[182:185], v161 offset:32768
	ds_read_b128 v[186:189], v161 offset:33792
	ds_read_b128 v[190:193], v161 offset:34816
	ds_read_b128 v[216:219], v161 offset:35840
	ds_read_b128 v[220:223], v161 offset:36864
	ds_read_b128 v[224:227], v161 offset:37888
	ds_read_b128 v[228:231], v161 offset:38912
	ds_read_b128 v[236:239], v161 offset:39936
	global_load_lds_dwordx4 v142, s[26:27]
	s_mov_b32 m0, s10
	s_nop 0
	global_load_lds_dwordx4 v144, s[26:27]
	s_waitcnt vmcnt(8)
	s_waitcnt lgkmcnt(0)
	s_barrier
	v_mfma_f32_16x16x32_bf16 v[126:129], v[130:133], v[182:185], v[126:129]
	v_mfma_f32_16x16x32_bf16 v[122:125], v[150:153], v[182:185], v[122:125]
	v_mfma_f32_16x16x32_bf16 v[110:113], v[130:133], v[190:193], v[110:113]
	v_mfma_f32_16x16x32_bf16 v[106:109], v[150:153], v[190:193], v[106:109]
	v_mfma_f32_16x16x32_bf16 v[94:97], v[130:133], v[220:223], v[94:97]
	v_mfma_f32_16x16x32_bf16 v[90:93], v[150:153], v[220:223], v[90:93]
	v_mfma_f32_16x16x32_bf16 v[78:81], v[130:133], v[228:231], v[78:81]
	v_mfma_f32_16x16x32_bf16 v[74:77], v[150:153], v[228:231], v[74:77]
	v_mfma_f32_16x16x32_bf16 v[126:129], v[146:149], v[186:189], v[126:129]
	v_mfma_f32_16x16x32_bf16 v[122:125], v[154:157], v[186:189], v[122:125]
	v_mfma_f32_16x16x32_bf16 v[110:113], v[146:149], v[216:219], v[110:113]
	v_mfma_f32_16x16x32_bf16 v[106:109], v[154:157], v[216:219], v[106:109]
	v_mfma_f32_16x16x32_bf16 v[94:97], v[146:149], v[224:227], v[94:97]
	v_mfma_f32_16x16x32_bf16 v[90:93], v[154:157], v[224:227], v[90:93]
	v_mfma_f32_16x16x32_bf16 v[78:81], v[146:149], v[236:239], v[78:81]
	v_mfma_f32_16x16x32_bf16 v[74:77], v[154:157], v[236:239], v[74:77]
	v_mfma_f32_16x16x32_bf16 v[118:121], v[162:165], v[182:185], v[118:121]
	v_mfma_f32_16x16x32_bf16 v[114:117], v[170:173], v[182:185], v[114:117]
	v_mfma_f32_16x16x32_bf16 v[102:105], v[162:165], v[190:193], v[102:105]
	v_mfma_f32_16x16x32_bf16 v[98:101], v[170:173], v[190:193], v[98:101]
	v_mfma_f32_16x16x32_bf16 v[86:89], v[162:165], v[220:223], v[86:89]
	v_mfma_f32_16x16x32_bf16 v[82:85], v[170:173], v[220:223], v[82:85]
	v_mfma_f32_16x16x32_bf16 v[70:73], v[162:165], v[228:231], v[70:73]
	v_mfma_f32_16x16x32_bf16 v[66:69], v[170:173], v[228:231], v[66:69]
	v_mfma_f32_16x16x32_bf16 v[118:121], v[166:169], v[186:189], v[118:121]
	v_mfma_f32_16x16x32_bf16 v[114:117], v[174:177], v[186:189], v[114:117]
	v_mfma_f32_16x16x32_bf16 v[102:105], v[166:169], v[216:219], v[102:105]
	v_mfma_f32_16x16x32_bf16 v[98:101], v[174:177], v[216:219], v[98:101]
	v_mfma_f32_16x16x32_bf16 v[86:89], v[166:169], v[224:227], v[86:89]
	v_mfma_f32_16x16x32_bf16 v[82:85], v[174:177], v[224:227], v[82:85]
	v_mfma_f32_16x16x32_bf16 v[70:73], v[166:169], v[236:239], v[70:73]
	v_mfma_f32_16x16x32_bf16 v[66:69], v[174:177], v[236:239], v[66:69]
	s_barrier
	s_add_i32 s22, s22, s30
	s_add_u32 vcc_lo, vcc_lo, s84
	s_addc_u32 vcc_hi, vcc_hi, s85
	s_add_u32 s26, s26, s84
	s_addc_u32 s27, s27, s85
	s_mov_b32 m0, s22
	ds_read_b128 v[182:185], v161 offset:49152
	ds_read_b128 v[186:189], v161 offset:50176
	ds_read_b128 v[190:193], v161 offset:51200
	ds_read_b128 v[216:219], v161 offset:52224
	ds_read_b128 v[220:223], v161 offset:53248
	ds_read_b128 v[224:227], v161 offset:54272
	ds_read_b128 v[228:231], v161 offset:55296
	ds_read_b128 v[236:239], v161 offset:56320
	global_load_lds_dwordx4 v136, vcc
	s_add_i32 m0, s22, 0x2000
	s_add_i32 s22, s23, s30
	global_load_lds_dwordx4 v140, vcc
	s_mov_b32 m0, s22
	s_nop 0
	global_load_lds_dwordx4 v253, vcc
	s_add_i32 m0, s22, 0x2000
	s_nop 0
	global_load_lds_dwordx4 v254, vcc
	s_mov_b32 m0, s18
	s_add_u32 s8, s8, 0x100
	global_load_lds_dwordx4 v134, s[26:27]
	s_mov_b32 m0, s19
	s_addc_u32 s9, s9, 0
	global_load_lds_dwordx4 v138, s[26:27]
	s_mov_b32 s26, s92
	s_cmp_ge_u32 s92, s12
	s_waitcnt vmcnt(8)
	s_waitcnt lgkmcnt(0)
	s_barrier
	v_mfma_f32_16x16x32_bf16 v[62:65], v[130:133], v[182:185], v[62:65]
	v_mfma_f32_16x16x32_bf16 v[58:61], v[150:153], v[182:185], v[58:61]
	v_mfma_f32_16x16x32_bf16 v[46:49], v[130:133], v[190:193], v[46:49]
	v_mfma_f32_16x16x32_bf16 v[42:45], v[150:153], v[190:193], v[42:45]
	v_mfma_f32_16x16x32_bf16 v[30:33], v[130:133], v[220:223], v[30:33]
	v_mfma_f32_16x16x32_bf16 v[26:29], v[150:153], v[220:223], v[26:29]
	v_mfma_f32_16x16x32_bf16 v[14:17], v[130:133], v[228:231], v[14:17]
	v_mfma_f32_16x16x32_bf16 v[10:13], v[150:153], v[228:231], v[10:13]
	v_mfma_f32_16x16x32_bf16 v[62:65], v[146:149], v[186:189], v[62:65]
	v_mfma_f32_16x16x32_bf16 v[58:61], v[154:157], v[186:189], v[58:61]
	v_mfma_f32_16x16x32_bf16 v[46:49], v[146:149], v[216:219], v[46:49]
	v_mfma_f32_16x16x32_bf16 v[42:45], v[154:157], v[216:219], v[42:45]
	v_mfma_f32_16x16x32_bf16 v[30:33], v[146:149], v[224:227], v[30:33]
	v_mfma_f32_16x16x32_bf16 v[26:29], v[154:157], v[224:227], v[26:29]
	v_mfma_f32_16x16x32_bf16 v[14:17], v[146:149], v[236:239], v[14:17]
	v_mfma_f32_16x16x32_bf16 v[10:13], v[154:157], v[236:239], v[10:13]
	v_mfma_f32_16x16x32_bf16 v[54:57], v[162:165], v[182:185], v[54:57]
	v_mfma_f32_16x16x32_bf16 v[50:53], v[170:173], v[182:185], v[50:53]
	v_mfma_f32_16x16x32_bf16 v[38:41], v[162:165], v[190:193], v[38:41]
	v_mfma_f32_16x16x32_bf16 v[34:37], v[170:173], v[190:193], v[34:37]
	v_mfma_f32_16x16x32_bf16 v[22:25], v[162:165], v[220:223], v[22:25]
	v_mfma_f32_16x16x32_bf16 v[18:21], v[170:173], v[220:223], v[18:21]
	v_mfma_f32_16x16x32_bf16 v[6:9], v[162:165], v[228:231], v[6:9]
	v_mfma_f32_16x16x32_bf16 v[2:5], v[170:173], v[228:231], v[2:5]
	v_mfma_f32_16x16x32_bf16 v[54:57], v[166:169], v[186:189], v[54:57]
	v_mfma_f32_16x16x32_bf16 v[50:53], v[174:177], v[186:189], v[50:53]
	v_mfma_f32_16x16x32_bf16 v[38:41], v[166:169], v[216:219], v[38:41]
	v_mfma_f32_16x16x32_bf16 v[34:37], v[174:177], v[216:219], v[34:37]
	v_mfma_f32_16x16x32_bf16 v[22:25], v[166:169], v[224:227], v[22:25]
	v_mfma_f32_16x16x32_bf16 v[18:21], v[174:177], v[224:227], v[18:21]
	v_mfma_f32_16x16x32_bf16 v[6:9], v[166:169], v[236:239], v[6:9]
	v_mfma_f32_16x16x32_bf16 v[2:5], v[174:177], v[236:239], v[2:5]
	s_barrier
	s_cbranch_scc0 .LBB0_215
	s_branch .Lgemm_after
; #define PG8_STAGE(bufoff, gbase, voff) do { _Pragma("unroll") for (int _i = 0; _i < 2; ++_i) \
;         __builtin_amdgcn_global_load_lds((const unsigned*)((const char*)(gbase) + (voff)[_i]), (LAS unsigned*)(lds + (bufoff) + ldsw + _i * 8192), 16, 0, 0); } while (0)
; #define PG8_LDA(dst, b, h) do { _Pragma("unroll") for (int m = 0; m < 4; ++m) _Pragma("unroll") for (int k = 0; k < 2; ++k) dst[m][k] = *(const LAS bf16x8*)(lds + PG8_SA(b, h) + aoff + m * 2048 + k * 1024); } while (0)
; #define PG8_LDB(dst, b, h) do { _Pragma("unroll") for (int n = 0; n < 2; ++n) _Pragma("unroll") for (int k = 0; k < 2; ++k) dst[n][k] = *(const LAS bf16x8*)(lds + PG8_SB(b, h) + boff + n * 2048 + k * 1024); } while (0)
; #define PG8_MMA(ai, bj, At, Bt) do { __builtin_amdgcn_s_setprio(1); _Pragma("unroll") for (int m = 0; m < 4; ++m) _Pragma("unroll") for (int n = 0; n < 2; ++n) _Pragma("unroll") for (int k = 0; k < 2; ++k) \
;         acc[ai][bj][m][n] = __builtin_amdgcn_mfma_f32_16x16x32_bf16(Bt[n][k], At[m][k], acc[ai][bj][m][n], 0, 0, 0); __builtin_amdgcn_s_setprio(0); } while (0)
; #define PG8_WAIT_V(n) asm volatile("s_waitcnt vmcnt(" #n ")" ::: "memory")
; #define PG8_WAIT_L(n) asm volatile("s_waitcnt lgkmcnt(" #n ")" ::: "memory")
; #define PG8_BAR __builtin_amdgcn_s_barrier()
; #define PG8_SCHED __builtin_amdgcn_sched_barrier(0)
; __device__ __forceinline__ void gemm_phase(LAS unsigned char* lds, const GemmD g, const Sched& S, const Epi& E) {
;     ...
;             const bool last = (t == nt - 2);
;             const char* a1 = cA + (size_t)(t + 1) * kstep;
;             const char* a2 = last ? nA : cA + (size_t)(t + 2) * kstep; const char* b2 = last ? nB : cB + (size_t)(t + 2) * kstep;
;             const char* a3 = a2 + kstep; const char* b3 = b2 + kstep;
;             PG8_LDB(B0, 0, 0); PG8_LDB(B1, 0, 1); PG8_SCHED; PG8_LDA(At, 0, 0); PG8_STAGE(PG8_SA(1, 1), a1 + hstepA, voffA);
;             PG8_WAIT_V(8); PG8_WAIT_L(0); PG8_BAR; PG8_MMA(0, 0, At, B0); PG8_MMA(0, 1, At, B1); PG8_BAR; PG8_SCHED;
;             PG8_LDA(At, 0, 1); PG8_STAGE(PG8_SB(0, 0), b2, voffB); PG8_STAGE(PG8_SB(0, 1), b2 + hstepB, voffB); PG8_STAGE(PG8_SA(0, 0), a2, voffA);
;             PG8_WAIT_V(8); PG8_WAIT_L(0); PG8_BAR; PG8_MMA(1, 0, At, B0); PG8_MMA(1, 1, At, B1); PG8_BAR; PG8_SCHED;
.LBB0_215:
	ds_read_b128 v[130:133], v240
	ds_read_b128 v[146:149], v240 offset:1024
	ds_read_b128 v[150:153], v240 offset:2048
	ds_read_b128 v[154:157], v240 offset:3072
	ds_read_b128 v[162:165], v241
	ds_read_b128 v[166:169], v241 offset:1024
	ds_read_b128 v[170:173], v241 offset:2048
	ds_read_b128 v[174:177], v241 offset:3072
	s_add_i32 m0, s31, 0xc000
	ds_read_b128 v[182:185], v161
	ds_read_b128 v[186:189], v161 offset:1024
	ds_read_b128 v[190:193], v161 offset:2048
	ds_read_b128 v[216:219], v161 offset:3072
	ds_read_b128 v[220:223], v161 offset:4096
	ds_read_b128 v[224:227], v161 offset:5120
	ds_read_b128 v[228:231], v161 offset:6144
	ds_read_b128 v[236:239], v161 offset:7168
	global_load_lds_dwordx4 v142, s[8:9]
	s_add_i32 m0, s31, 0xe000
	s_nop 0
	global_load_lds_dwordx4 v144, s[8:9]
	s_add_i32 s92, s26, 2
	s_add_u32 s93, s8, 0x80
	s_addc_u32 s27, s9, 0
	s_add_i32 s22, 0, 0x10000
	s_cmp_eq_u32 s11, s26
	s_cselect_b32 s27, s1, s27
	s_cselect_b32 s26, s0, s93
	s_cselect_b32 vcc_hi, s17, s35
	s_cselect_b32 vcc_lo, s16, s34
	s_add_i32 s23, 0, 0x14000
	s_waitcnt vmcnt(8)
	s_waitcnt lgkmcnt(0)
	s_barrier
	v_mfma_f32_16x16x32_bf16 v[126:129], v[130:133], v[182:185], v[126:129]
	v_mfma_f32_16x16x32_bf16 v[122:125], v[150:153], v[182:185], v[122:125]
	v_mfma_f32_16x16x32_bf16 v[110:113], v[130:133], v[190:193], v[110:113]
	v_mfma_f32_16x16x32_bf16 v[106:109], v[150:153], v[190:193], v[106:109]
	v_mfma_f32_16x16x32_bf16 v[94:97], v[130:133], v[220:223], v[94:97]
	v_mfma_f32_16x16x32_bf16 v[90:93], v[150:153], v[220:223], v[90:93]
	v_mfma_f32_16x16x32_bf16 v[78:81], v[130:133], v[228:231], v[78:81]
	v_mfma_f32_16x16x32_bf16 v[74:77], v[150:153], v[228:231], v[74:77]
	v_mfma_f32_16x16x32_bf16 v[126:129], v[146:149], v[186:189], v[126:129]
	v_mfma_f32_16x16x32_bf16 v[122:125], v[154:157], v[186:189], v[122:125]
	v_mfma_f32_16x16x32_bf16 v[110:113], v[146:149], v[216:219], v[110:113]
	v_mfma_f32_16x16x32_bf16 v[106:109], v[154:157], v[216:219], v[106:109]
	v_mfma_f32_16x16x32_bf16 v[94:97], v[146:149], v[224:227], v[94:97]
	v_mfma_f32_16x16x32_bf16 v[90:93], v[154:157], v[224:227], v[90:93]
	v_mfma_f32_16x16x32_bf16 v[78:81], v[146:149], v[236:239], v[78:81]
	v_mfma_f32_16x16x32_bf16 v[74:77], v[154:157], v[236:239], v[74:77]
	v_mfma_f32_16x16x32_bf16 v[118:121], v[162:165], v[182:185], v[118:121]
	v_mfma_f32_16x16x32_bf16 v[114:117], v[170:173], v[182:185], v[114:117]
	v_mfma_f32_16x16x32_bf16 v[102:105], v[162:165], v[190:193], v[102:105]
	v_mfma_f32_16x16x32_bf16 v[98:101], v[170:173], v[190:193], v[98:101]
	v_mfma_f32_16x16x32_bf16 v[86:89], v[162:165], v[220:223], v[86:89]
	v_mfma_f32_16x16x32_bf16 v[82:85], v[170:173], v[220:223], v[82:85]
	v_mfma_f32_16x16x32_bf16 v[70:73], v[162:165], v[228:231], v[70:73]
	v_mfma_f32_16x16x32_bf16 v[66:69], v[170:173], v[228:231], v[66:69]
	v_mfma_f32_16x16x32_bf16 v[118:121], v[166:169], v[186:189], v[118:121]
	v_mfma_f32_16x16x32_bf16 v[114:117], v[174:177], v[186:189], v[114:117]
	v_mfma_f32_16x16x32_bf16 v[102:105], v[166:169], v[216:219], v[102:105]
	v_mfma_f32_16x16x32_bf16 v[98:101], v[174:177], v[216:219], v[98:101]
	v_mfma_f32_16x16x32_bf16 v[86:89], v[166:169], v[224:227], v[86:89]
	v_mfma_f32_16x16x32_bf16 v[82:85], v[174:177], v[224:227], v[82:85]
	v_mfma_f32_16x16x32_bf16 v[70:73], v[166:169], v[236:239], v[70:73]
	v_mfma_f32_16x16x32_bf16 v[66:69], v[174:177], v[236:239], v[66:69]
	s_barrier
	s_add_i32 s22, s22, s30
	s_mov_b32 m0, s22
	ds_read_b128 v[182:185], v161 offset:16384
	ds_read_b128 v[186:189], v161 offset:17408
	ds_read_b128 v[190:193], v161 offset:18432
	ds_read_b128 v[216:219], v161 offset:19456
	ds_read_b128 v[220:223], v161 offset:20480
	ds_read_b128 v[224:227], v161 offset:21504
	ds_read_b128 v[228:231], v161 offset:22528
	ds_read_b128 v[236:239], v161 offset:23552
	global_load_lds_dwordx4 v136, vcc
	s_add_i32 m0, s22, 0x2000
	s_add_i32 s22, s23, s30
	global_load_lds_dwordx4 v140, vcc
	s_mov_b32 m0, s22
	s_nop 0
	global_load_lds_dwordx4 v253, vcc
	s_add_i32 m0, s22, 0x2000
	s_nop 0
	global_load_lds_dwordx4 v254, vcc
	s_mov_b32 m0, s31
	s_add_u32 s34, s34, 0x100
	global_load_lds_dwordx4 v134, s[26:27]
	s_mov_b32 m0, s14
	s_addc_u32 s35, s35, 0
	global_load_lds_dwordx4 v138, s[26:27]
	s_waitcnt vmcnt(8)
	s_waitcnt lgkmcnt(0)
	s_barrier
	v_mfma_f32_16x16x32_bf16 v[62:65], v[130:133], v[182:185], v[62:65]
	v_mfma_f32_16x16x32_bf16 v[58:61], v[150:153], v[182:185], v[58:61]
	v_mfma_f32_16x16x32_bf16 v[46:49], v[130:133], v[190:193], v[46:49]
	v_mfma_f32_16x16x32_bf16 v[42:45], v[150:153], v[190:193], v[42:45]
	v_mfma_f32_16x16x32_bf16 v[30:33], v[130:133], v[220:223], v[30:33]
	v_mfma_f32_16x16x32_bf16 v[26:29], v[150:153], v[220:223], v[26:29]
	v_mfma_f32_16x16x32_bf16 v[14:17], v[130:133], v[228:231], v[14:17]
	v_mfma_f32_16x16x32_bf16 v[10:13], v[150:153], v[228:231], v[10:13]
	v_mfma_f32_16x16x32_bf16 v[62:65], v[146:149], v[186:189], v[62:65]
	v_mfma_f32_16x16x32_bf16 v[58:61], v[154:157], v[186:189], v[58:61]
	v_mfma_f32_16x16x32_bf16 v[46:49], v[146:149], v[216:219], v[46:49]
	v_mfma_f32_16x16x32_bf16 v[42:45], v[154:157], v[216:219], v[42:45]
	v_mfma_f32_16x16x32_bf16 v[30:33], v[146:149], v[224:227], v[30:33]
	v_mfma_f32_16x16x32_bf16 v[26:29], v[154:157], v[224:227], v[26:29]
	v_mfma_f32_16x16x32_bf16 v[14:17], v[146:149], v[236:239], v[14:17]
	v_mfma_f32_16x16x32_bf16 v[10:13], v[154:157], v[236:239], v[10:13]
	v_mfma_f32_16x16x32_bf16 v[54:57], v[162:165], v[182:185], v[54:57]
	v_mfma_f32_16x16x32_bf16 v[50:53], v[170:173], v[182:185], v[50:53]
	v_mfma_f32_16x16x32_bf16 v[38:41], v[162:165], v[190:193], v[38:41]
	v_mfma_f32_16x16x32_bf16 v[34:37], v[170:173], v[190:193], v[34:37]
	v_mfma_f32_16x16x32_bf16 v[22:25], v[162:165], v[220:223], v[22:25]
	v_mfma_f32_16x16x32_bf16 v[18:21], v[170:173], v[220:223], v[18:21]
	v_mfma_f32_16x16x32_bf16 v[6:9], v[162:165], v[228:231], v[6:9]
	v_mfma_f32_16x16x32_bf16 v[2:5], v[170:173], v[228:231], v[2:5]
	v_mfma_f32_16x16x32_bf16 v[54:57], v[166:169], v[186:189], v[54:57]
	v_mfma_f32_16x16x32_bf16 v[50:53], v[174:177], v[186:189], v[50:53]
	v_mfma_f32_16x16x32_bf16 v[38:41], v[166:169], v[216:219], v[38:41]
	v_mfma_f32_16x16x32_bf16 v[34:37], v[174:177], v[216:219], v[34:37]
	v_mfma_f32_16x16x32_bf16 v[22:25], v[166:169], v[224:227], v[22:25]
	v_mfma_f32_16x16x32_bf16 v[18:21], v[174:177], v[224:227], v[18:21]
	v_mfma_f32_16x16x32_bf16 v[6:9], v[166:169], v[236:239], v[6:9]
	v_mfma_f32_16x16x32_bf16 v[2:5], v[174:177], v[236:239], v[2:5]
	s_barrier
; #define PG8_STAGE(bufoff, gbase, voff) do { _Pragma("unroll") for (int _i = 0; _i < 2; ++_i) \
;         __builtin_amdgcn_global_load_lds((const unsigned*)((const char*)(gbase) + (voff)[_i]), (LAS unsigned*)(lds + (bufoff) + ldsw + _i * 8192), 16, 0, 0); } while (0)
; #define PG8_LDA(dst, b, h) do { _Pragma("unroll") for (int m = 0; m < 4; ++m) _Pragma("unroll") for (int k = 0; k < 2; ++k) dst[m][k] = *(const LAS bf16x8*)(lds + PG8_SA(b, h) + aoff + m * 2048 + k * 1024); } while (0)
; #define PG8_LDB(dst, b, h) do { _Pragma("unroll") for (int n = 0; n < 2; ++n) _Pragma("unroll") for (int k = 0; k < 2; ++k) dst[n][k] = *(const LAS bf16x8*)(lds + PG8_SB(b, h) + boff + n * 2048 + k * 1024); } while (0)
; #define PG8_MMA(ai, bj, At, Bt) do { __builtin_amdgcn_s_setprio(1); _Pragma("unroll") for (int m = 0; m < 4; ++m) _Pragma("unroll") for (int n = 0; n < 2; ++n) _Pragma("unroll") for (int k = 0; k < 2; ++k) \
;         acc[ai][bj][m][n] = __builtin_amdgcn_mfma_f32_16x16x32_bf16(Bt[n][k], At[m][k], acc[ai][bj][m][n], 0, 0, 0); __builtin_amdgcn_s_setprio(0); } while (0)
; #define PG8_WAIT_V(n) asm volatile("s_waitcnt vmcnt(" #n ")" ::: "memory")
; #define PG8_WAIT_L(n) asm volatile("s_waitcnt lgkmcnt(" #n ")" ::: "memory")
; #define PG8_BAR __builtin_amdgcn_s_barrier()
; #define PG8_SCHED __builtin_amdgcn_sched_barrier(0)
; __device__ __forceinline__ void gemm_phase(LAS unsigned char* lds, const GemmD g, const Sched& S, const Epi& E) {
;     ...
;             PG8_LDB(B0, 1, 0); PG8_LDB(B1, 1, 1); PG8_SCHED; PG8_LDA(At, 1, 0); PG8_STAGE(PG8_SA(0, 1), a2 + hstepA, voffA);
;             PG8_WAIT_V(8); PG8_WAIT_L(0); PG8_BAR; PG8_MMA(0, 0, At, B0); PG8_MMA(0, 1, At, B1); PG8_BAR; PG8_SCHED;
;             PG8_LDA(At, 1, 1); PG8_STAGE(PG8_SB(1, 0), b3, voffB); PG8_STAGE(PG8_SB(1, 1), b3 + hstepB, voffB); PG8_STAGE(PG8_SA(1, 0), a3, voffA);
;             PG8_WAIT_V(8); PG8_WAIT_L(0); PG8_BAR; PG8_MMA(1, 0, At, B0); PG8_MMA(1, 1, At, B1); PG8_BAR; PG8_SCHED;
;         }
	s_add_i32 s22, 0, 0x18000
	s_add_i32 s23, 0, 0x1c000
	ds_read_b128 v[130:133], v242
	ds_read_b128 v[146:149], v242 offset:1024
	ds_read_b128 v[150:153], v242 offset:2048
	ds_read_b128 v[154:157], v242 offset:3072
	ds_read_b128 v[162:165], v243
	ds_read_b128 v[166:169], v243 offset:1024
	ds_read_b128 v[170:173], v243 offset:2048
	ds_read_b128 v[174:177], v243 offset:3072
	s_mov_b32 m0, s15
	ds_read_b128 v[182:185], v161 offset:32768
	ds_read_b128 v[186:189], v161 offset:33792
	ds_read_b128 v[190:193], v161 offset:34816
	ds_read_b128 v[216:219], v161 offset:35840
	ds_read_b128 v[220:223], v161 offset:36864
	ds_read_b128 v[224:227], v161 offset:37888
	ds_read_b128 v[228:231], v161 offset:38912
	ds_read_b128 v[236:239], v161 offset:39936
	global_load_lds_dwordx4 v142, s[26:27]
	s_mov_b32 m0, s10
	s_nop 0
	global_load_lds_dwordx4 v144, s[26:27]
	s_waitcnt vmcnt(8)
	s_waitcnt lgkmcnt(0)
	s_barrier
	v_mfma_f32_16x16x32_bf16 v[126:129], v[130:133], v[182:185], v[126:129]
	v_mfma_f32_16x16x32_bf16 v[122:125], v[150:153], v[182:185], v[122:125]
	v_mfma_f32_16x16x32_bf16 v[110:113], v[130:133], v[190:193], v[110:113]
	v_mfma_f32_16x16x32_bf16 v[106:109], v[150:153], v[190:193], v[106:109]
	v_mfma_f32_16x16x32_bf16 v[94:97], v[130:133], v[220:223], v[94:97]
	v_mfma_f32_16x16x32_bf16 v[90:93], v[150:153], v[220:223], v[90:93]
	v_mfma_f32_16x16x32_bf16 v[78:81], v[130:133], v[228:231], v[78:81]
	v_mfma_f32_16x16x32_bf16 v[74:77], v[150:153], v[228:231], v[74:77]
	v_mfma_f32_16x16x32_bf16 v[126:129], v[146:149], v[186:189], v[126:129]
	v_mfma_f32_16x16x32_bf16 v[122:125], v[154:157], v[186:189], v[122:125]
	v_mfma_f32_16x16x32_bf16 v[110:113], v[146:149], v[216:219], v[110:113]
	v_mfma_f32_16x16x32_bf16 v[106:109], v[154:157], v[216:219], v[106:109]
	v_mfma_f32_16x16x32_bf16 v[94:97], v[146:149], v[224:227], v[94:97]
	v_mfma_f32_16x16x32_bf16 v[90:93], v[154:157], v[224:227], v[90:93]
	v_mfma_f32_16x16x32_bf16 v[78:81], v[146:149], v[236:239], v[78:81]
	v_mfma_f32_16x16x32_bf16 v[74:77], v[154:157], v[236:239], v[74:77]
	v_mfma_f32_16x16x32_bf16 v[118:121], v[162:165], v[182:185], v[118:121]
	v_mfma_f32_16x16x32_bf16 v[114:117], v[170:173], v[182:185], v[114:117]
	v_mfma_f32_16x16x32_bf16 v[102:105], v[162:165], v[190:193], v[102:105]
	v_mfma_f32_16x16x32_bf16 v[98:101], v[170:173], v[190:193], v[98:101]
	v_mfma_f32_16x16x32_bf16 v[86:89], v[162:165], v[220:223], v[86:89]
	v_mfma_f32_16x16x32_bf16 v[82:85], v[170:173], v[220:223], v[82:85]
	v_mfma_f32_16x16x32_bf16 v[70:73], v[162:165], v[228:231], v[70:73]
	v_mfma_f32_16x16x32_bf16 v[66:69], v[170:173], v[228:231], v[66:69]
	v_mfma_f32_16x16x32_bf16 v[118:121], v[166:169], v[186:189], v[118:121]
	v_mfma_f32_16x16x32_bf16 v[114:117], v[174:177], v[186:189], v[114:117]
	v_mfma_f32_16x16x32_bf16 v[102:105], v[166:169], v[216:219], v[102:105]
	v_mfma_f32_16x16x32_bf16 v[98:101], v[174:177], v[216:219], v[98:101]
	v_mfma_f32_16x16x32_bf16 v[86:89], v[166:169], v[224:227], v[86:89]
	v_mfma_f32_16x16x32_bf16 v[82:85], v[174:177], v[224:227], v[82:85]
	v_mfma_f32_16x16x32_bf16 v[70:73], v[166:169], v[236:239], v[70:73]
	v_mfma_f32_16x16x32_bf16 v[66:69], v[174:177], v[236:239], v[66:69]
	s_barrier
	s_add_i32 s22, s22, s30
	s_add_u32 vcc_lo, vcc_lo, s84
	s_addc_u32 vcc_hi, vcc_hi, s85
	s_add_u32 s26, s26, s84
	s_addc_u32 s27, s27, s85
	s_mov_b32 m0, s22
	ds_read_b128 v[182:185], v161 offset:49152
	ds_read_b128 v[186:189], v161 offset:50176
	ds_read_b128 v[190:193], v161 offset:51200
	ds_read_b128 v[216:219], v161 offset:52224
	ds_read_b128 v[220:223], v161 offset:53248
	ds_read_b128 v[224:227], v161 offset:54272
	ds_read_b128 v[228:231], v161 offset:55296
	ds_read_b128 v[236:239], v161 offset:56320
	global_load_lds_dwordx4 v136, vcc
	s_add_i32 m0, s22, 0x2000
	s_add_i32 s22, s23, s30
	global_load_lds_dwordx4 v140, vcc
	s_mov_b32 m0, s22
	s_nop 0
	global_load_lds_dwordx4 v253, vcc
	s_add_i32 m0, s22, 0x2000
	s_nop 0
	global_load_lds_dwordx4 v254, vcc
	s_mov_b32 m0, s18
	s_add_u32 s8, s8, 0x100
	global_load_lds_dwordx4 v134, s[26:27]
	s_mov_b32 m0, s19
	s_addc_u32 s9, s9, 0
	global_load_lds_dwordx4 v138, s[26:27]
	s_mov_b32 s26, s92
	s_cmp_ge_u32 s92, s12
	s_waitcnt vmcnt(8)
	s_waitcnt lgkmcnt(0)
	s_barrier
	v_mfma_f32_16x16x32_bf16 v[62:65], v[130:133], v[182:185], v[62:65]
	v_mfma_f32_16x16x32_bf16 v[58:61], v[150:153], v[182:185], v[58:61]
	v_mfma_f32_16x16x32_bf16 v[46:49], v[130:133], v[190:193], v[46:49]
	v_mfma_f32_16x16x32_bf16 v[42:45], v[150:153], v[190:193], v[42:45]
	v_mfma_f32_16x16x32_bf16 v[30:33], v[130:133], v[220:223], v[30:33]
	v_mfma_f32_16x16x32_bf16 v[26:29], v[150:153], v[220:223], v[26:29]
	v_mfma_f32_16x16x32_bf16 v[14:17], v[130:133], v[228:231], v[14:17]
	v_mfma_f32_16x16x32_bf16 v[10:13], v[150:153], v[228:231], v[10:13]
	v_mfma_f32_16x16x32_bf16 v[62:65], v[146:149], v[186:189], v[62:65]
	v_mfma_f32_16x16x32_bf16 v[58:61], v[154:157], v[186:189], v[58:61]
	v_mfma_f32_16x16x32_bf16 v[46:49], v[146:149], v[216:219], v[46:49]
	v_mfma_f32_16x16x32_bf16 v[42:45], v[154:157], v[216:219], v[42:45]
	v_mfma_f32_16x16x32_bf16 v[30:33], v[146:149], v[224:227], v[30:33]
	v_mfma_f32_16x16x32_bf16 v[26:29], v[154:157], v[224:227], v[26:29]
	v_mfma_f32_16x16x32_bf16 v[14:17], v[146:149], v[236:239], v[14:17]
	v_mfma_f32_16x16x32_bf16 v[10:13], v[154:157], v[236:239], v[10:13]
	v_mfma_f32_16x16x32_bf16 v[54:57], v[162:165], v[182:185], v[54:57]
	v_mfma_f32_16x16x32_bf16 v[50:53], v[170:173], v[182:185], v[50:53]
	v_mfma_f32_16x16x32_bf16 v[38:41], v[162:165], v[190:193], v[38:41]
	v_mfma_f32_16x16x32_bf16 v[34:37], v[170:173], v[190:193], v[34:37]
	v_mfma_f32_16x16x32_bf16 v[22:25], v[162:165], v[220:223], v[22:25]
	v_mfma_f32_16x16x32_bf16 v[18:21], v[170:173], v[220:223], v[18:21]
	v_mfma_f32_16x16x32_bf16 v[6:9], v[162:165], v[228:231], v[6:9]
	v_mfma_f32_16x16x32_bf16 v[2:5], v[170:173], v[228:231], v[2:5]
	v_mfma_f32_16x16x32_bf16 v[54:57], v[166:169], v[186:189], v[54:57]
	v_mfma_f32_16x16x32_bf16 v[50:53], v[174:177], v[186:189], v[50:53]
	v_mfma_f32_16x16x32_bf16 v[38:41], v[166:169], v[216:219], v[38:41]
	v_mfma_f32_16x16x32_bf16 v[34:37], v[174:177], v[216:219], v[34:37]
	v_mfma_f32_16x16x32_bf16 v[22:25], v[166:169], v[224:227], v[22:25]
	v_mfma_f32_16x16x32_bf16 v[18:21], v[174:177], v[224:227], v[18:21]
	v_mfma_f32_16x16x32_bf16 v[6:9], v[166:169], v[236:239], v[6:9]
	v_mfma_f32_16x16x32_bf16 v[2:5], v[174:177], v[236:239], v[2:5]
	s_barrier
	s_cbranch_scc0 .LBB0_215

; template <bool COOP>
; __global__ void __launch_bounds__(512, 2) fwd_kernel(Params p) {
;     ...
; }
.LBB0_641:
	s_nop 0
	s_nop 0
	s_nop 0
	s_nop 0
	s_nop 0
	s_nop 0
	s_nop 0
	s_nop 0
	s_nop 0
	s_nop 0
	s_nop 0
	s_nop 0
	s_nop 0
	s_nop 0
	s_nop 0
	s_nop 0
	s_nop 0
	s_nop 0
	s_nop 0
	s_nop 0
	s_nop 0
	s_nop 0
	s_nop 0
	s_nop 0
	s_nop 0
	s_nop 0
	s_nop 0
	s_nop 0
	s_nop 0
	s_nop 0
	s_nop 0
	s_nop 0
	s_nop 0
	s_nop 0
	s_nop 0
	s_nop 0
	s_nop 0
	s_nop 0
	s_nop 0
	s_nop 0
	s_nop 0
	s_nop 0
	s_nop 0
	s_nop 0
	s_nop 0
	s_nop 0
	s_nop 0
	s_nop 0
	s_nop 0
	s_nop 0
	s_nop 0
	s_nop 0
	s_nop 0
	s_nop 0
	s_nop 0
	s_nop 0
	s_nop 0
	s_nop 0
	s_nop 0
	s_nop 0
	s_nop 0
	s_nop 0
	s_nop 0
	s_nop 0
	s_nop 0
	s_nop 0
	s_nop 0
	s_nop 0
	s_nop 0
	s_nop 0
	s_nop 0
	s_nop 0
	s_nop 0
	s_nop 0
	s_nop 0
	s_nop 0
	s_nop 0
	s_nop 0
	s_nop 0
	s_nop 0
	s_nop 0
	s_nop 0
	s_nop 0
	s_nop 0
	s_nop 0
	s_nop 0
	s_nop 0
	s_nop 0
	s_nop 0
	s_nop 0
	s_nop 0
	s_nop 0
	s_nop 0
	s_nop 0
	s_nop 0
	s_nop 0
	s_nop 0
	s_nop 0
	s_nop 0
	s_nop 0
	s_nop 0
	s_nop 0
	s_nop 0
	s_nop 0
	s_nop 0
	s_nop 0
	s_nop 0
	s_nop 0
	s_nop 0
	s_nop 0
	s_nop 0
	s_nop 0
	s_nop 0
	s_nop 0
	s_nop 0
	s_nop 0
	s_nop 0
	s_nop 0
	s_nop 0
	s_nop 0
	s_nop 0
	s_nop 0
	s_nop 0
	s_nop 0
	s_nop 0
	s_nop 0
	s_nop 0
	s_nop 0
	s_nop 0
	s_nop 0
	s_nop 0
	s_nop 0
	s_nop 0
	s_nop 0
	s_nop 0
	s_nop 0
	s_nop 0
	s_nop 0
	s_nop 0
	s_nop 0
	s_nop 0
	s_nop 0
	s_nop 0
	s_nop 0
	s_nop 0
	s_nop 0
	s_nop 0
	s_nop 0
	s_nop 0
	s_nop 0
	s_nop 0
	s_nop 0
	s_nop 0
	s_nop 0
	s_nop 0
	s_nop 0
	s_nop 0
	s_nop 0
	s_nop 0
	s_nop 0
	s_nop 0
	s_nop 0
	s_nop 0
	s_nop 0
	s_nop 0
	s_nop 0
	s_nop 0
	s_nop 0
	s_nop 0
	s_nop 0
	s_nop 0
	s_nop 0
	s_nop 0
	s_nop 0
	s_nop 0
	s_nop 0
	s_nop 0
	s_nop 0
	s_nop 0
	s_nop 0
	s_nop 0
	s_nop 0
	s_nop 0
	s_nop 0
	s_nop 0
	s_nop 0
	s_nop 0
	s_nop 0
	s_nop 0
	s_nop 0
	s_nop 0
	s_nop 0
	s_nop 0
	s_nop 0
	s_nop 0
	s_nop 0
	s_nop 0
	s_nop 0
	s_nop 0
	s_nop 0
	s_nop 0
	s_nop 0
	s_nop 0
	s_nop 0
	s_nop 0
	s_nop 0
	s_nop 0
	s_nop 0
	s_nop 0
	s_nop 0
	s_nop 0
	s_nop 0
	s_nop 0
	s_nop 0
	s_nop 0
	s_nop 0
	s_nop 0
	s_nop 0
	s_nop 0
	s_nop 0
	s_nop 0
	s_nop 0
	s_nop 0
	s_nop 0
	s_nop 0
	s_nop 0
	s_nop 0
	s_nop 0
	s_nop 0
	s_nop 0
	s_nop 0
	s_nop 0
	s_nop 0
	s_nop 0
	s_nop 0
	s_nop 0
	s_nop 0
	s_nop 0
	s_nop 0
	s_nop 0
	s_nop 0
	s_nop 0
	s_nop 0
	s_nop 0
	s_nop 0
	s_nop 0
	s_nop 0
	s_nop 0
	s_nop 0
	s_nop 0
	s_nop 0
	s_nop 0
	s_nop 0
	s_nop 0
	s_nop 0
	s_nop 0
	s_nop 0
	s_nop 0
	s_nop 0
	s_nop 0
	s_nop 0
	s_nop 0
	s_nop 0
	s_nop 0
	s_nop 0
	s_nop 0
	s_nop 0
	s_nop 0
	s_nop 0
	s_nop 0
	s_nop 0
	s_nop 0
	s_nop 0
	s_nop 0
	s_nop 0
	s_nop 0
	s_nop 0
	s_nop 0
	s_nop 0
	s_nop 0
	s_nop 0
	s_nop 0
	s_nop 0
	s_nop 0
	s_nop 0
	s_nop 0
	s_nop 0
	s_nop 0
	s_nop 0
	s_nop 0
	s_nop 0
	s_nop 0
	s_nop 0
	s_nop 0
	s_nop 0
	s_nop 0
	s_nop 0
	s_nop 0
	s_nop 0
	s_nop 0
	s_nop 0
	s_nop 0
	s_nop 0
	s_nop 0
	s_nop 0
	s_nop 0
	s_endpgm
